# baseline (speedup 1.0000x reference)
.LBB0_176:
	s_or_b64 exec, exec, s[6:7]
	v_cmp_eq_u32_e32 vcc, 0, v131
	s_and_saveexec_b64 s[6:7], vcc
	s_cbranch_execz .Lubc_skip
	s_waitcnt vmcnt(0)
	ds_write_b32 v129, v243 offset:61440
	s_waitcnt lgkmcnt(0)

.LBB0_178:
	s_barrier
	ds_read_b32 v0, v129 offset:61440
	s_movk_i32 s3, 0x7ff
	s_mov_b64 s[6:7], -1
	s_waitcnt lgkmcnt(0)
	s_barrier
	v_cmp_lt_u32_e32 vcc, s3, v0
	v_readfirstlane_b32 s2, v0
	s_cbranch_vccnz .LBB0_177
	v_mov_b32_e32 v0, v131
	s_nop 0
	v_cmp_eq_u32_e32 vcc, 0, v0
	s_and_saveexec_b64 s[6:7], vcc
	s_cbranch_execz .LBB0_183
	s_mov_b64 s[10:11], exec
	v_mbcnt_lo_u32_b32 v0, s10, 0
	v_mbcnt_hi_u32_b32 v0, s11, v0
	v_cmp_eq_u32_e32 vcc, 0, v0
	s_and_saveexec_b64 s[8:9], vcc
	s_cbranch_execz .LBB0_182
	s_bcnt1_i32_b64 s3, s[10:11]
	v_readlane_b32 s10, v255, 27
	v_mov_b32_e32 v1, s3
	v_readlane_b32 s11, v255, 28
	s_nop 4
	global_atomic_add v243, v129, v1, s[10:11] sc0
